# DSA logits: LDS operand reads kept three k-steps ahead across the 16-key group boundaries (rows of the next group parked early)
# baseline (speedup 1.0000x reference)
; #define LAS __attribute__((address_space(3)))
;     ...
;       for (int b = 0; b < nb; ++b) {
;           float lgv[4], rsv[4];
; #pragma unroll
;           for (int jj = 0; jj < 4; ++jj) {
;               const int rho = jj * 16 + c16, slot = b * 64 + rho;
;               f32x4 a = {0.f, 0.f, 0.f, 0.f}; float ss = 0.f;
; #pragma unroll
;               for (int ks = 0; ks < 4; ++ks) {
; #pragma unroll
;                   for (int e = 0; e < 4; ++e) asm("v_dot2_f32_bf16 %0, %1, %1, %0" : "+v"(ss) : "v"(w[jj][ks][e]));
;                   a = __builtin_amdgcn_mfma_f32_16x16x32_bf16(qa[ks], *reinterpret_cast<const bf16x8*>(&w[jj][ks]), a, 0, 0, 0);
;                   *(LAS u32x4*)(wbase + rho * 256 + (((ks * 4 + quad) ^ fsw) << 4)) = w[jj][ks]; }
;               ss += __shfl_xor(ss, 16); ss += __shfl_xor(ss, 32);
;               const float rstd = rsqrtf(ss * (1.f / 128.f) + EPS);
;               const float av = quad == 0 ? a[0] : (quad == 1 ? a[1] : (quad == 2 ? a[2] : a[3]));
;               rsv[jj] = rstd; lgv[jj] = (slot < kcount) ? av * rstd * 0.08838834764831845f : -__builtin_inff();
;           }
;           if (b + 1 < nb) gl(b + 1);
.LBB0_928:
	s_add_i32 s0, s24, 1
	s_cmp_ge_i32 s0, s23
	s_cbranch_scc0 .Ldsa_steady
; #define LAS __attribute__((address_space(3)))
;     ...
;       for (int b = 0; b < nb; ++b) {
;           float lgv[4], rsv[4];
; #pragma unroll
;           for (int jj = 0; jj < 4; ++jj) {
;               const int rho = jj * 16 + c16, slot = b * 64 + rho;
;               f32x4 a = {0.f, 0.f, 0.f, 0.f}; float ss = 0.f;
; #pragma unroll
;               for (int ks = 0; ks < 4; ++ks) {
; #pragma unroll
;                   for (int e = 0; e < 4; ++e) asm("v_dot2_f32_bf16 %0, %1, %1, %0" : "+v"(ss) : "v"(w[jj][ks][e]));
;                   a = __builtin_amdgcn_mfma_f32_16x16x32_bf16(qa[ks], *reinterpret_cast<const bf16x8*>(&w[jj][ks]), a, 0, 0, 0);
;                   *(LAS u32x4*)(wbase + rho * 256 + (((ks * 4 + quad) ^ fsw) << 4)) = w[jj][ks]; }
;               ss += __shfl_xor(ss, 16); ss += __shfl_xor(ss, 32);
;               const float rstd = rsqrtf(ss * (1.f / 128.f) + EPS);
;               const float av = quad == 0 ? a[0] : (quad == 1 ? a[1] : (quad == 2 ? a[2] : a[3]));
;               rsv[jj] = rstd; lgv[jj] = (slot < kcount) ? av * rstd * 0.08838834764831845f : -__builtin_inff();
;           }
	s_waitcnt vmcnt(12)
	ds_write_b128 v244, v[26:29]
	ds_write_b128 v245, v[18:21]
	ds_write_b128 v246, v[22:25]
	ds_write_b128 v247, v[30:33]
	v_add_u32_e32 v0, v146, v147
	ds_read_b128 v[232:235], v0
	v_add_u32_e32 v0, v146, v148
	ds_read_b128 v[236:239], v0
	v_add_u32_e32 v0, v146, v149
	ds_read_b128 v[240:243], v0
	s_waitcnt vmcnt(8)
	ds_write_b128 v244, v[42:45] offset:4096
	ds_write_b128 v245, v[34:37] offset:4096
	ds_write_b128 v246, v[38:41] offset:4096
	ds_write_b128 v247, v[46:49] offset:4096
	v_mov_b32_e32 v118, 0
	s_waitcnt lgkmcnt(6)
	v_dot2_f32_bf16 v118, v232, v232, v118
	v_dot2_f32_bf16 v118, v233, v233, v118
	v_dot2_f32_bf16 v118, v234, v234, v118
	v_dot2_f32_bf16 v118, v235, v235, v118
	v_mfma_f32_16x16x32_bf16 v[114:117], v[2:5], v[232:235], 0
	v_add_u32_e32 v0, v146, v150
	ds_read_b128 v[232:235], v0
	s_waitcnt lgkmcnt(6)
	v_dot2_f32_bf16 v118, v236, v236, v118
	v_dot2_f32_bf16 v118, v237, v237, v118
	v_dot2_f32_bf16 v118, v238, v238, v118
	v_dot2_f32_bf16 v118, v239, v239, v118
	v_mfma_f32_16x16x32_bf16 v[114:117], v[6:9], v[236:239], v[114:117]
	v_add_u32_e32 v0, v146, v147
	ds_read_b128 v[236:239], v0 offset:4096
	s_waitcnt lgkmcnt(6)
	v_dot2_f32_bf16 v118, v240, v240, v118
	v_dot2_f32_bf16 v118, v241, v241, v118
	v_dot2_f32_bf16 v118, v242, v242, v118
	v_dot2_f32_bf16 v118, v243, v243, v118
	v_mfma_f32_16x16x32_bf16 v[114:117], v[10:13], v[240:243], v[114:117]
	v_add_u32_e32 v0, v146, v148
	ds_read_b128 v[240:243], v0 offset:4096
	s_waitcnt lgkmcnt(2)
	v_dot2_f32_bf16 v118, v232, v232, v118
	v_dot2_f32_bf16 v118, v233, v233, v118
	v_dot2_f32_bf16 v118, v234, v234, v118
	v_dot2_f32_bf16 v118, v235, v235, v118
	v_mfma_f32_16x16x32_bf16 v[114:117], v[14:17], v[232:235], v[114:117]
	v_add_u32_e32 v0, v146, v149
	ds_read_b128 v[232:235], v0 offset:4096
	s_nop 2
	v_mov_b32_e32 v119, v118
	s_nop 1
	v_permlane16_swap_b32_e32 v118, v119
	v_add_f32_e32 v161, v118, v119
	ds_bpermute_b32 v172, v248, v161
	v_cndmask_b32_e64 v114, v114, v115, s[66:67]
	v_cndmask_b32_e64 v114, v114, v116, s[40:41]
	v_cndmask_b32_e64 v114, v114, v117, s[68:69]
	s_waitcnt vmcnt(4)
	ds_write_b128 v244, v[58:61] offset:8192
	ds_write_b128 v245, v[50:53] offset:8192
	ds_write_b128 v246, v[54:57] offset:8192
	ds_write_b128 v247, v[62:65] offset:8192
	v_mov_b32_e32 v115, 0
	s_waitcnt lgkmcnt(7)
	v_dot2_f32_bf16 v115, v236, v236, v115
	v_dot2_f32_bf16 v115, v237, v237, v115
	v_dot2_f32_bf16 v115, v238, v238, v115
	v_dot2_f32_bf16 v115, v239, v239, v115
	v_mfma_f32_16x16x32_bf16 v[116:119], v[2:5], v[236:239], 0
	v_add_u32_e32 v0, v146, v150
	ds_read_b128 v[236:239], v0 offset:4096
	s_waitcnt lgkmcnt(7)
	v_dot2_f32_bf16 v115, v240, v240, v115
	v_dot2_f32_bf16 v115, v241, v241, v115
	v_dot2_f32_bf16 v115, v242, v242, v115
	v_dot2_f32_bf16 v115, v243, v243, v115
	v_mfma_f32_16x16x32_bf16 v[116:119], v[6:9], v[240:243], v[116:119]
	v_add_u32_e32 v0, v146, v147
	ds_read_b128 v[240:243], v0 offset:8192
	s_waitcnt lgkmcnt(7)
	v_dot2_f32_bf16 v115, v232, v232, v115
	v_dot2_f32_bf16 v115, v233, v233, v115
	v_dot2_f32_bf16 v115, v234, v234, v115
	v_dot2_f32_bf16 v115, v235, v235, v115
	v_mfma_f32_16x16x32_bf16 v[116:119], v[10:13], v[232:235], v[116:119]
	v_add_u32_e32 v0, v146, v148
	ds_read_b128 v[232:235], v0 offset:8192
	s_waitcnt lgkmcnt(2)
	v_dot2_f32_bf16 v115, v236, v236, v115
	v_dot2_f32_bf16 v115, v237, v237, v115
	v_dot2_f32_bf16 v115, v238, v238, v115
	v_dot2_f32_bf16 v115, v239, v239, v115
	v_mfma_f32_16x16x32_bf16 v[116:119], v[14:17], v[236:239], v[116:119]
	v_add_u32_e32 v0, v146, v149
	ds_read_b128 v[236:239], v0 offset:8192
	s_nop 2
	v_mov_b32_e32 v120, v115
	s_nop 1
	v_permlane16_swap_b32_e32 v115, v120
	v_add_f32_e32 v115, v115, v120
	ds_bpermute_b32 v173, v248, v115
	v_cndmask_b32_e64 v116, v116, v117, s[66:67]
	v_cndmask_b32_e64 v116, v116, v118, s[40:41]
	v_cndmask_b32_e64 v116, v116, v119, s[68:69]
	s_waitcnt vmcnt(0)
	ds_write_b128 v244, v[74:77] offset:12288
	ds_write_b128 v245, v[66:69] offset:12288
	ds_write_b128 v246, v[70:73] offset:12288
	ds_write_b128 v247, v[78:81] offset:12288
	v_mov_b32_e32 v117, 0
	s_waitcnt lgkmcnt(7)
	v_dot2_f32_bf16 v117, v240, v240, v117
	v_dot2_f32_bf16 v117, v241, v241, v117
	v_dot2_f32_bf16 v117, v242, v242, v117
	v_dot2_f32_bf16 v117, v243, v243, v117
	v_mfma_f32_16x16x32_bf16 v[118:121], v[2:5], v[240:243], 0
	v_add_u32_e32 v0, v146, v150
	ds_read_b128 v[240:243], v0 offset:8192
	s_waitcnt lgkmcnt(7)
	v_dot2_f32_bf16 v117, v232, v232, v117
	v_dot2_f32_bf16 v117, v233, v233, v117
	v_dot2_f32_bf16 v117, v234, v234, v117
	v_dot2_f32_bf16 v117, v235, v235, v117
	v_mfma_f32_16x16x32_bf16 v[118:121], v[6:9], v[232:235], v[118:121]
	v_add_u32_e32 v0, v146, v147
	ds_read_b128 v[232:235], v0 offset:12288
	s_waitcnt lgkmcnt(7)
	v_dot2_f32_bf16 v117, v236, v236, v117
	v_dot2_f32_bf16 v117, v237, v237, v117
	v_dot2_f32_bf16 v117, v238, v238, v117
	v_dot2_f32_bf16 v117, v239, v239, v117
	v_mfma_f32_16x16x32_bf16 v[118:121], v[10:13], v[236:239], v[118:121]
	v_add_u32_e32 v0, v146, v148
	ds_read_b128 v[236:239], v0 offset:12288
	s_waitcnt lgkmcnt(2)
	v_dot2_f32_bf16 v117, v240, v240, v117
	v_dot2_f32_bf16 v117, v241, v241, v117
	v_dot2_f32_bf16 v117, v242, v242, v117
	v_dot2_f32_bf16 v117, v243, v243, v117
	v_mfma_f32_16x16x32_bf16 v[118:121], v[14:17], v[240:243], v[118:121]
	v_add_u32_e32 v0, v146, v149
	ds_read_b128 v[240:243], v0 offset:12288
	s_nop 2
	v_mov_b32_e32 v123, v117
	s_nop 1
	v_permlane16_swap_b32_e32 v117, v123
	v_add_f32_e32 v117, v117, v123
	ds_bpermute_b32 v174, v248, v117
	v_cndmask_b32_e64 v118, v118, v119, s[66:67]
	v_cndmask_b32_e64 v118, v118, v120, s[40:41]
	v_cndmask_b32_e64 v118, v118, v121, s[68:69]
	v_mov_b32_e32 v119, 0
	s_waitcnt lgkmcnt(3)
	v_dot2_f32_bf16 v119, v232, v232, v119
	v_dot2_f32_bf16 v119, v233, v233, v119
	v_dot2_f32_bf16 v119, v234, v234, v119
	v_dot2_f32_bf16 v119, v235, v235, v119
	v_mfma_f32_16x16x32_bf16 v[176:179], v[2:5], v[232:235], 0
	v_add_u32_e32 v0, v146, v150
	ds_read_b128 v[232:235], v0 offset:12288
	s_waitcnt lgkmcnt(3)
	v_dot2_f32_bf16 v119, v236, v236, v119
	v_dot2_f32_bf16 v119, v237, v237, v119
	v_dot2_f32_bf16 v119, v238, v238, v119
	v_dot2_f32_bf16 v119, v239, v239, v119
	v_mfma_f32_16x16x32_bf16 v[176:179], v[6:9], v[236:239], v[176:179]
	s_waitcnt lgkmcnt(2)
	v_dot2_f32_bf16 v119, v240, v240, v119
	v_dot2_f32_bf16 v119, v241, v241, v119
	v_dot2_f32_bf16 v119, v242, v242, v119
	v_dot2_f32_bf16 v119, v243, v243, v119
	v_mfma_f32_16x16x32_bf16 v[176:179], v[10:13], v[240:243], v[176:179]
	s_waitcnt lgkmcnt(0)
	v_dot2_f32_bf16 v119, v232, v232, v119
	v_dot2_f32_bf16 v119, v233, v233, v119
	v_dot2_f32_bf16 v119, v234, v234, v119
	v_dot2_f32_bf16 v119, v235, v235, v119
	v_mfma_f32_16x16x32_bf16 v[120:123], v[14:17], v[232:235], v[176:179]
	s_nop 2
	v_mov_b32_e32 v0, v119
	s_nop 1
	v_permlane16_swap_b32_e32 v119, v0
	v_add_f32_e32 v119, v119, v0
	ds_bpermute_b32 v175, v248, v119
	v_cndmask_b32_e64 v120, v120, v121, s[66:67]
	v_cndmask_b32_e64 v120, v120, v122, s[40:41]
	v_cndmask_b32_e64 v120, v120, v123, s[68:69]
	s_add_i32 s24, s24, 1

; #define LAS __attribute__((address_space(3)))
;     ...
;       auto gl = [&](int b) {
; #pragma unroll
;           for (int jj = 0; jj < 4; ++jj) { const int kx = list[(b * 4 + jj) * 16 + c16] & 4095; const u16* cp = prow + (size_t)kx * NP + C_BC + quad * 8;
; #pragma unroll
;               for (int ks = 0; ks < 4; ++ks) w[jj][ks] = *(const u32x4*)(cp + ks * 32); } };
;       if (nb > 0) gl(0);
;       for (int b = 0; b < nb; ++b) {
;           float lgv[4], rsv[4];
; #pragma unroll
;           for (int jj = 0; jj < 4; ++jj) {
;               const int rho = jj * 16 + c16, slot = b * 64 + rho;
;               f32x4 a = {0.f, 0.f, 0.f, 0.f}; float ss = 0.f;
; #pragma unroll
;               for (int ks = 0; ks < 4; ++ks) {
; #pragma unroll
;                   for (int e = 0; e < 4; ++e) asm("v_dot2_f32_bf16 %0, %1, %1, %0" : "+v"(ss) : "v"(w[jj][ks][e]));
;                   a = __builtin_amdgcn_mfma_f32_16x16x32_bf16(qa[ks], *reinterpret_cast<const bf16x8*>(&w[jj][ks]), a, 0, 0, 0);
;                   *(LAS u32x4*)(wbase + rho * 256 + (((ks * 4 + quad) ^ fsw) << 4)) = w[jj][ks]; }
;               ss += __shfl_xor(ss, 16); ss += __shfl_xor(ss, 32);
;               const float rstd = rsqrtf(ss * (1.f / 128.f) + EPS);
;               const float av = quad == 0 ? a[0] : (quad == 1 ? a[1] : (quad == 2 ? a[2] : a[3]));
;               rsv[jj] = rstd; lgv[jj] = (slot < kcount) ? av * rstd * 0.08838834764831845f : -__builtin_inff();
;           }
;           if (b + 1 < nb) gl(b + 1);
.Ldsa_steady:
	ds_read_u16 v232, v154
	ds_read_u16 v234, v154 offset:32
	ds_read_u16 v236, v154 offset:64
	ds_read_u16 v238, v154 offset:96
	v_mov_b32_e32 v240, v249
	v_mov_b32_e32 v241, 0
	v_mov_b32_e32 v233, 0
	v_mov_b32_e32 v235, 0
	v_mov_b32_e32 v237, 0
	v_mov_b32_e32 v239, 0
	s_mov_b64 s[0:1], 0x1000
	v_lshl_add_u64 v[242:243], s[54:55], 0, v[240:241]
	v_lshl_add_u64 v[242:243], v[242:243], 0, s[0:1]
	s_waitcnt lgkmcnt(0)
	v_and_b32_e32 v232, 0xfff, v232
	v_mul_u32_u24_e32 v232, 0x5800, v232
	v_lshl_add_u64 v[224:225], v[232:233], 0, v[242:243]
	v_and_b32_e32 v234, 0xfff, v234
	v_mul_u32_u24_e32 v234, 0x5800, v234
	v_lshl_add_u64 v[226:227], v[234:235], 0, v[242:243]
	v_and_b32_e32 v236, 0xfff, v236
	v_mul_u32_u24_e32 v236, 0x5800, v236
	v_lshl_add_u64 v[228:229], v[236:237], 0, v[242:243]
	v_and_b32_e32 v238, 0xfff, v238
	v_mul_u32_u24_e32 v238, 0x5800, v238
	v_lshl_add_u64 v[230:231], v[238:239], 0, v[242:243]
	s_waitcnt vmcnt(12)
	ds_write_b128 v244, v[26:29]
	ds_write_b128 v245, v[18:21]
	ds_write_b128 v246, v[22:25]
	ds_write_b128 v247, v[30:33]
	global_load_dwordx4 v[18:21], v[224:225], off offset:64
	global_load_dwordx4 v[22:25], v[224:225], off offset:128
	global_load_dwordx4 v[26:29], v[224:225], off
	global_load_dwordx4 v[30:33], v[224:225], off offset:192
	v_add_u32_e32 v0, v146, v147
	ds_read_b128 v[232:235], v0
	v_add_u32_e32 v0, v146, v148
	ds_read_b128 v[236:239], v0
	v_add_u32_e32 v0, v146, v149
	ds_read_b128 v[240:243], v0
	s_waitcnt vmcnt(12)
	ds_write_b128 v244, v[42:45] offset:4096
	ds_write_b128 v245, v[34:37] offset:4096
	ds_write_b128 v246, v[38:41] offset:4096
	ds_write_b128 v247, v[46:49] offset:4096
	global_load_dwordx4 v[34:37], v[226:227], off offset:64
	global_load_dwordx4 v[38:41], v[226:227], off offset:128
	global_load_dwordx4 v[42:45], v[226:227], off
	global_load_dwordx4 v[46:49], v[226:227], off offset:192
	v_mov_b32_e32 v118, 0
	s_waitcnt lgkmcnt(6)
	v_dot2_f32_bf16 v118, v232, v232, v118
	v_dot2_f32_bf16 v118, v233, v233, v118
	v_dot2_f32_bf16 v118, v234, v234, v118
	v_dot2_f32_bf16 v118, v235, v235, v118
	v_mfma_f32_16x16x32_bf16 v[114:117], v[2:5], v[232:235], 0
	v_add_u32_e32 v0, v146, v150
	ds_read_b128 v[232:235], v0
	s_waitcnt lgkmcnt(6)
	v_dot2_f32_bf16 v118, v236, v236, v118
	v_dot2_f32_bf16 v118, v237, v237, v118
	v_dot2_f32_bf16 v118, v238, v238, v118
	v_dot2_f32_bf16 v118, v239, v239, v118
	v_mfma_f32_16x16x32_bf16 v[114:117], v[6:9], v[236:239], v[114:117]
	v_add_u32_e32 v0, v146, v147
	ds_read_b128 v[236:239], v0 offset:4096
	s_waitcnt lgkmcnt(6)
	v_dot2_f32_bf16 v118, v240, v240, v118
	v_dot2_f32_bf16 v118, v241, v241, v118
	v_dot2_f32_bf16 v118, v242, v242, v118
	v_dot2_f32_bf16 v118, v243, v243, v118
	v_mfma_f32_16x16x32_bf16 v[114:117], v[10:13], v[240:243], v[114:117]
	v_add_u32_e32 v0, v146, v148
	ds_read_b128 v[240:243], v0 offset:4096
	s_waitcnt lgkmcnt(2)
	v_dot2_f32_bf16 v118, v232, v232, v118
	v_dot2_f32_bf16 v118, v233, v233, v118
	v_dot2_f32_bf16 v118, v234, v234, v118
	v_dot2_f32_bf16 v118, v235, v235, v118
	v_mfma_f32_16x16x32_bf16 v[114:117], v[14:17], v[232:235], v[114:117]
	v_add_u32_e32 v0, v146, v149
	ds_read_b128 v[232:235], v0 offset:4096
	s_nop 2
	v_mov_b32_e32 v119, v118
	s_nop 1
	v_permlane16_swap_b32_e32 v118, v119
	v_add_f32_e32 v161, v118, v119
	ds_bpermute_b32 v172, v248, v161
	v_cndmask_b32_e64 v114, v114, v115, s[66:67]
	v_cndmask_b32_e64 v114, v114, v116, s[40:41]
	v_cndmask_b32_e64 v114, v114, v117, s[68:69]
	s_waitcnt vmcnt(12)
	ds_write_b128 v244, v[58:61] offset:8192
	ds_write_b128 v245, v[50:53] offset:8192
	ds_write_b128 v246, v[54:57] offset:8192
	ds_write_b128 v247, v[62:65] offset:8192
	global_load_dwordx4 v[50:53], v[228:229], off offset:64
	global_load_dwordx4 v[54:57], v[228:229], off offset:128
	global_load_dwordx4 v[58:61], v[228:229], off
	global_load_dwordx4 v[62:65], v[228:229], off offset:192
	v_mov_b32_e32 v115, 0
	s_waitcnt lgkmcnt(7)
	v_dot2_f32_bf16 v115, v236, v236, v115
	v_dot2_f32_bf16 v115, v237, v237, v115
	v_dot2_f32_bf16 v115, v238, v238, v115
	v_dot2_f32_bf16 v115, v239, v239, v115
	v_mfma_f32_16x16x32_bf16 v[116:119], v[2:5], v[236:239], 0
	v_add_u32_e32 v0, v146, v150
	ds_read_b128 v[236:239], v0 offset:4096
	s_waitcnt lgkmcnt(7)
	v_dot2_f32_bf16 v115, v240, v240, v115
	v_dot2_f32_bf16 v115, v241, v241, v115
	v_dot2_f32_bf16 v115, v242, v242, v115
	v_dot2_f32_bf16 v115, v243, v243, v115
	v_mfma_f32_16x16x32_bf16 v[116:119], v[6:9], v[240:243], v[116:119]
	v_add_u32_e32 v0, v146, v147
	ds_read_b128 v[240:243], v0 offset:8192
	s_waitcnt lgkmcnt(7)
; #define LAS __attribute__((address_space(3)))
;     ...
;       for (int b = 0; b < nb; ++b) {
;           float lgv[4], rsv[4];
; #pragma unroll
;           for (int jj = 0; jj < 4; ++jj) {
;               const int rho = jj * 16 + c16, slot = b * 64 + rho;
;               f32x4 a = {0.f, 0.f, 0.f, 0.f}; float ss = 0.f;
; #pragma unroll
;               for (int ks = 0; ks < 4; ++ks) {
; #pragma unroll
;                   for (int e = 0; e < 4; ++e) asm("v_dot2_f32_bf16 %0, %1, %1, %0" : "+v"(ss) : "v"(w[jj][ks][e]));
;                   a = __builtin_amdgcn_mfma_f32_16x16x32_bf16(qa[ks], *reinterpret_cast<const bf16x8*>(&w[jj][ks]), a, 0, 0, 0);
;                   *(LAS u32x4*)(wbase + rho * 256 + (((ks * 4 + quad) ^ fsw) << 4)) = w[jj][ks]; }
;               ss += __shfl_xor(ss, 16); ss += __shfl_xor(ss, 32);
;               const float rstd = rsqrtf(ss * (1.f / 128.f) + EPS);
;               const float av = quad == 0 ? a[0] : (quad == 1 ? a[1] : (quad == 2 ? a[2] : a[3]));
;               rsv[jj] = rstd; lgv[jj] = (slot < kcount) ? av * rstd * 0.08838834764831845f : -__builtin_inff();
;           }
;           if (b + 1 < nb) gl(b + 1);
	v_dot2_f32_bf16 v115, v232, v232, v115
	v_dot2_f32_bf16 v115, v233, v233, v115
	v_dot2_f32_bf16 v115, v234, v234, v115
	v_dot2_f32_bf16 v115, v235, v235, v115
	v_mfma_f32_16x16x32_bf16 v[116:119], v[10:13], v[232:235], v[116:119]
	v_add_u32_e32 v0, v146, v148
	ds_read_b128 v[232:235], v0 offset:8192
	s_waitcnt lgkmcnt(2)
	v_dot2_f32_bf16 v115, v236, v236, v115
	v_dot2_f32_bf16 v115, v237, v237, v115
	v_dot2_f32_bf16 v115, v238, v238, v115
	v_dot2_f32_bf16 v115, v239, v239, v115
	v_mfma_f32_16x16x32_bf16 v[116:119], v[14:17], v[236:239], v[116:119]
	v_add_u32_e32 v0, v146, v149
	ds_read_b128 v[236:239], v0 offset:8192
	s_nop 2
	v_mov_b32_e32 v120, v115
	s_nop 1
	v_permlane16_swap_b32_e32 v115, v120
	v_add_f32_e32 v115, v115, v120
	ds_bpermute_b32 v173, v248, v115
	v_cndmask_b32_e64 v116, v116, v117, s[66:67]
	v_cndmask_b32_e64 v116, v116, v118, s[40:41]
	v_cndmask_b32_e64 v116, v116, v119, s[68:69]
	s_waitcnt vmcnt(12)
	ds_write_b128 v244, v[74:77] offset:12288
	ds_write_b128 v245, v[66:69] offset:12288
	ds_write_b128 v246, v[70:73] offset:12288
	ds_write_b128 v247, v[78:81] offset:12288
	global_load_dwordx4 v[66:69], v[230:231], off offset:64
	global_load_dwordx4 v[70:73], v[230:231], off offset:128
	global_load_dwordx4 v[74:77], v[230:231], off
	global_load_dwordx4 v[78:81], v[230:231], off offset:192
	v_mov_b32_e32 v117, 0
	s_waitcnt lgkmcnt(7)
	v_dot2_f32_bf16 v117, v240, v240, v117
	v_dot2_f32_bf16 v117, v241, v241, v117
	v_dot2_f32_bf16 v117, v242, v242, v117
	v_dot2_f32_bf16 v117, v243, v243, v117
	v_mfma_f32_16x16x32_bf16 v[118:121], v[2:5], v[240:243], 0
	v_add_u32_e32 v0, v146, v150
	ds_read_b128 v[240:243], v0 offset:8192
	s_waitcnt lgkmcnt(7)
	v_dot2_f32_bf16 v117, v232, v232, v117
	v_dot2_f32_bf16 v117, v233, v233, v117
	v_dot2_f32_bf16 v117, v234, v234, v117
	v_dot2_f32_bf16 v117, v235, v235, v117
	v_mfma_f32_16x16x32_bf16 v[118:121], v[6:9], v[232:235], v[118:121]
	v_add_u32_e32 v0, v146, v147
	ds_read_b128 v[232:235], v0 offset:12288
	s_waitcnt lgkmcnt(7)
	v_dot2_f32_bf16 v117, v236, v236, v117
	v_dot2_f32_bf16 v117, v237, v237, v117
	v_dot2_f32_bf16 v117, v238, v238, v117
	v_dot2_f32_bf16 v117, v239, v239, v117
	v_mfma_f32_16x16x32_bf16 v[118:121], v[10:13], v[236:239], v[118:121]
	v_add_u32_e32 v0, v146, v148
	ds_read_b128 v[236:239], v0 offset:12288
	s_waitcnt lgkmcnt(2)
	v_dot2_f32_bf16 v117, v240, v240, v117
	v_dot2_f32_bf16 v117, v241, v241, v117
	v_dot2_f32_bf16 v117, v242, v242, v117
	v_dot2_f32_bf16 v117, v243, v243, v117
	v_mfma_f32_16x16x32_bf16 v[118:121], v[14:17], v[240:243], v[118:121]
	v_add_u32_e32 v0, v146, v149
	ds_read_b128 v[240:243], v0 offset:12288
	s_nop 2
	v_mov_b32_e32 v123, v117
	s_nop 1
	v_permlane16_swap_b32_e32 v117, v123
	v_add_f32_e32 v117, v117, v123
	ds_bpermute_b32 v174, v248, v117
	v_cndmask_b32_e64 v118, v118, v119, s[66:67]
	v_cndmask_b32_e64 v118, v118, v120, s[40:41]
	v_cndmask_b32_e64 v118, v118, v121, s[68:69]
	v_mov_b32_e32 v119, 0
	s_waitcnt lgkmcnt(3)
	v_dot2_f32_bf16 v119, v232, v232, v119
	v_dot2_f32_bf16 v119, v233, v233, v119
	v_dot2_f32_bf16 v119, v234, v234, v119
	v_dot2_f32_bf16 v119, v235, v235, v119
	v_mfma_f32_16x16x32_bf16 v[176:179], v[2:5], v[232:235], 0
	v_add_u32_e32 v0, v146, v150
	ds_read_b128 v[232:235], v0 offset:12288
	s_waitcnt lgkmcnt(3)
	v_dot2_f32_bf16 v119, v236, v236, v119
	v_dot2_f32_bf16 v119, v237, v237, v119
	v_dot2_f32_bf16 v119, v238, v238, v119
	v_dot2_f32_bf16 v119, v239, v239, v119
	v_mfma_f32_16x16x32_bf16 v[176:179], v[6:9], v[236:239], v[176:179]
	s_waitcnt lgkmcnt(2)
	v_dot2_f32_bf16 v119, v240, v240, v119
	v_dot2_f32_bf16 v119, v241, v241, v119
	v_dot2_f32_bf16 v119, v242, v242, v119
	v_dot2_f32_bf16 v119, v243, v243, v119
	v_mfma_f32_16x16x32_bf16 v[176:179], v[10:13], v[240:243], v[176:179]
	s_waitcnt lgkmcnt(0)
	v_dot2_f32_bf16 v119, v232, v232, v119
	v_dot2_f32_bf16 v119, v233, v233, v119
	v_dot2_f32_bf16 v119, v234, v234, v119
	v_dot2_f32_bf16 v119, v235, v235, v119
	v_mfma_f32_16x16x32_bf16 v[120:123], v[14:17], v[232:235], v[176:179]
	s_nop 2
	v_mov_b32_e32 v0, v119
	s_nop 1
	v_permlane16_swap_b32_e32 v119, v0
	v_add_f32_e32 v119, v119, v0
	ds_bpermute_b32 v175, v248, v119
	v_cndmask_b32_e64 v120, v120, v121, s[66:67]
	v_cndmask_b32_e64 v120, v120, v122, s[40:41]
	v_cndmask_b32_e64 v120, v120, v123, s[68:69]
	s_add_i32 s24, s24, 1
	s_branch .LBB0_946
